# v118 + XCD-aware unit map for the stick-breaking attention units (4 query chunks of a (batch, head) on one XCD, G==256 guarded)
# speedup vs baseline: 1.0046x; 1.0046x over previous
; __device__ __forceinline__ void attention_phase(const Params& p, LAS unsigned char* lds, int G, int blk) {
;     ...
;     const int v = (G % 8 == 0) ? (blk % 8) * (G / 8) + blk / 8 : blk;
;     for (int rep = 0; rep < PROBE_DIFF_REPS; ++rep)
;     for (int u = v; u < 1024; u += G) {
;         const int bh = (u & 255) >> 2, s = u & 3, i = u >> 8;
;         const int qb = (i == 0) ? s : (i == 1) ? 7 - s : (i == 2) ? 8 + s : 15 - s;
;     ...
;         diff_unit(p, lds, bh >> 3, bh & 7, qb, lam);
;     ...
;     }
;     for (int rep = 0; rep < PROBE_SB_REPS; ++rep)
;     for (int u = v; u < 1024; u += G) {
;         const int bh = (u & 255) >> 2, s = u & 3, i = u >> 8;
;         const int qb = (i == 0) ? s : (i == 1) ? 7 - s : (i == 2) ? 8 + s : 15 - s;
;     ...
;         sb_unit(p, lds, bh >> 3, bh & 7, qb);
.LBB0_315:
	s_cmpk_lg_u32 s30, 0x100
	s_cbranch_scc1 .Lxcd_ident_sb
	s_and_b32 s0, s16, 7
	s_lshl_b32 s0, s0, 2
	s_bfe_u32 s1, s16, 0x20003
	s_or_b32 s0, s0, s1
	s_and_b32 s1, s16, 0xe0
	s_or_b32 s16, s0, s1
